# v006 + phase id computed with SALU arithmetic instead of a per-phase global byte load
# speedup vs baseline: 1.0041x; 1.0041x over previous
; __global__ void __launch_bounds__(512, 2) fwd_megakernel(Params p_, int ph_lo, int ph_hi) {
;     ...
;     for (int phi = ph_lo; phi < ph_hi; ++phi) {
;         const int ph = phase_seq[phi];
;         int tid = threadIdx.x; asm volatile("" : "+v"(tid));
;         unsigned long long kab = (unsigned long long)__builtin_amdgcn_kernarg_segment_ptr(); asm volatile("" : "+s"(kab));
;         const Params& p = *(const Params*)(const __attribute__((address_space(4))) char*)kab;
;         const int lane = tid & 63, wave = __builtin_amdgcn_readfirstlane(tid >> 6);
;         int G = gridDim.x, bx = blockIdx.x; asm volatile("" : "+s"(G), "+s"(bx));
;         unsigned char* ws = p.ws;
;         bf16_t* xb = (bf16_t*)(ws + WS_XB); bf16_t* act = (bf16_t*)(ws + WS_ACT); bf16_t* zb = act; bf16_t* cat = (bf16_t*)(ws + WS_CAT);
;         bf16_t* memkv = (bf16_t*)(ws + WS_MEMKV); float* ssq = (float*)(ws + WS_SSQ);
;         float* X = p.out;
;         if (ph == 0) {
;             prologue(p, lds, bx * 8 + wave, G * 8, wave, lane);
;         } else if (ph < 17) {
;             const int q = ph - 1, layer = q >> 3, s = q & 7;
;             const int ldz = layer == 0 ? NMIX0 : NMIX1, qmoff = layer == 0 ? 1536 : 2304;
;             if (s == 0 || s == 6) {
;                 const int mat = layer * 2 + (s == 6);
;                 pg8::Gemm g{xb, (const bf16_t*)(ws + WS_WFFIN + mat * SZ_WFFIN), T, 2 * FF, DM};
;                 pg8::Order S; S.init(T, 2 * FF, G, bx);
;                 pg8::EpiSwiglu E{act, ssq};
;                 pg8::gemm_phase<pg8::EpiSwiglu>(lds, g, S, E, tid);
;             } else if (s == 1 || s == 7 || s == 5) {
.LBB0_16:
	v_readlane_b32 s2, v255, 0
	v_mov_b32_e32 v218, v180
	s_mov_b64 s[0:1], s[64:65]
	s_mov_b32 s45, s63
	s_mov_b32 s44, s2
	s_load_dwordx4 s[16:19], s[0:1], 0xa0
	v_readlane_b32 s3, v255, 1
	s_mov_b32 s97, s20
	v_and_b32_e32 v190, 63, v218
	v_readfirstlane_b32 s46, v218
	s_cmp_gt_u32 s20, 3
	s_cselect_b32 s4, 1, 0
	s_cmp_gt_u32 s20, 10
	s_cselect_b32 s5, 1, 0
	s_add_i32 s4, s4, s20
	s_add_i32 s4, s4, s5
	s_waitcnt lgkmcnt(0)
	s_add_u32 s14, s18, 0x5080000
	s_addc_u32 s15, s19, 0
	s_add_u32 s28, s18, 0x19080000
	s_addc_u32 s29, s19, 0
	s_cmp_lg_u32 s4, 0
	s_mov_b64 s[2:3], -1
	s_cbranch_scc0 .LBB0_326
	s_and_b32 s31, 0xffff, s4
	s_cmp_gt_u32 s31, 16
	s_cbranch_scc1 .LBB0_325
	s_add_i32 s8, s31, -1
	s_and_b32 s47, s8, 7
	s_add_u32 s24, s18, 0x9880000
	s_addc_u32 s25, s19, 0
	s_cmp_lt_i32 s47, 6
	s_cbranch_scc1 .LBB0_20
	s_cmp_lg_u32 s47, 6
	s_cselect_b64 s[4:5], -1, 0
	s_cbranch_execz .LBB0_21
	s_branch .LBB0_22
